# attention V tile in LDS: unpadded 128-B rows with XOR chunk swizzle (conflict-free for the real ds_read_b128 lane groups) on top of two-block K/V lookahead and PV read ring
# speedup vs baseline: 1.0145x; 1.0051x over previous
; #define LAS __attribute__((address_space(3)))
; __device__ __forceinline__ int opaque_tid() { int t = threadIdx.x; asm volatile("" : "+v"(t)); return t; }
; __device__ __forceinline__ void ph_attn(const Params& p, LAS unsigned char* lds) {
;     const int tid = opaque_tid(), lane = tid & 63, w = __builtin_amdgcn_readfirstlane(tid >> 6), fr = lane & 15, fq = lane >> 4;
;     unsigned char* ws = p.ws; const bf16_t* qb = (const bf16_t*)(ws + WS_A); const bf16_t* kb = (const bf16_t*)(ws + WS_KB); const bf16_t* vt = (const bf16_t*)(ws + WS_VT); bf16_t* ao = (bf16_t*)(ws + WS_B);
;     constexpr int PR = 36864;
;     LAS unsigned char* pw = lds + PR + w * 8448 + fr * 528 + fq * 8;
;     const unsigned koff = (unsigned)((tid >> 5) * 1024 + (tid & 31) * 8);
;     const unsigned voff = (unsigned)((tid >> 3) * 256 + (tid & 7) * 8);
;     LAS unsigned char* kst = lds + (tid >> 5) * 528 + (tid & 31) * 16;
;     LAS unsigned char* vst = lds + (tid >> 3) * 144 + (tid & 7) * 16;
;     const LAS unsigned char* krd = lds + fr * 528 + fq * 16;
;     const LAS unsigned char* vrd = lds + fr * 144 + fq * 16;
.LBB0_1080:
	s_cmp_lt_i32 s94, 9
	s_cselect_b64 s[0:1], -1, 0
	s_and_b64 s[4:5], s[0:1], s[4:5]
	s_andn2_b64 vcc, exec, s[4:5]
	s_cbranch_vccnz .LBB0_1110
	v_mov_b32_e32 v0, v200
	s_cmpk_gt_i32 s2, 0x43f
	s_nop 0
	v_readfirstlane_b32 s4, v0
	s_cbranch_scc1 .LBB0_1110
	s_add_u32 s6, s92, 0x11680000
	s_addc_u32 s7, s93, 0
	s_add_u32 s3, s92, 0x19c80000
	s_addc_u32 s14, s93, 0
	s_add_u32 s15, s92, 0x1a880000
	s_addc_u32 s20, s93, 0
	s_add_u32 s8, s92, 0x15780000
	s_addc_u32 s9, s93, 0
	s_ashr_i32 s4, s4, 6
	s_waitcnt lgkmcnt(0)
	v_and_b32_e32 v1, 15, v0
	s_waitcnt vmcnt(0)
	v_bfe_u32 v3, v0, 4, 2
	s_mul_i32 s5, s4, 0x2100
	v_ashrrev_i32_e32 v4, 5, v0
	v_and_b32_e32 v6, 31, v0
	v_ashrrev_i32_e32 v7, 3, v0
	v_and_b32_e32 v0, 7, v0
	s_add_i32 s10, s5, 0
	v_lshlrev_b32_e32 v11, 4, v0
	v_lshlrev_b32_e32 v0, 3, v0
	s_movk_i32 s12, 0x210
	v_mov_b32_e32 v2, s10
	s_movk_i32 s10, 0x90
	v_lshl_or_b32 v180, v7, 8, v0
	v_lshlrev_b32_e32 v0, 3, v6
	v_mad_u32_u24 v5, v1, s12, v2
	v_lshlrev_b32_e32 v2, 3, v3
	v_mul_lo_u32 v8, v4, s12
	v_mul_lo_u32 v10, v7, s10
	v_mad_u32_u24 v12, v1, s12, 0
	v_lshlrev_b32_e32 v13, 4, v3
	s_movk_i32 s10, 0xfe80
	v_lshl_or_b32 v182, v4, 10, v0
	s_lshl_b32 s21, s4, 4
	v_lshlrev_b32_e32 v4, 2, v3
	v_mov_b32_e32 v3, s5
	v_add_u32_e32 v193, v12, v13
	v_mad_i32_i24 v12, v1, s10, v12
	v_or_b32_e32 v196, s21, v1
	v_mad_u32_u24 v1, v1, s12, v3
	v_mov_b32_e32 v0, 0
	v_add3_u32 v1, v1, v13, 0
	v_add_u32_e32 v8, 0, v8
	v_lshlrev_b32_e32 v9, 4, v6
	v_add_u32_e32 v10, 0, v10
	v_mov_b32_e32 v181, v0
	v_add_u32_e32 v197, 0x9000, v1
	v_mbcnt_lo_u32_b32 v1, -1, 0
	s_mov_b32 s11, 0
	v_mov_b32_e32 v183, v0
	v_lshl_add_u64 v[184:185], v[180:181], 1, s[92:93]
	s_mov_b32 s22, 0x8000
	v_lshlrev_b32_e32 v186, 1, v2
	s_mov_b32 s23, 0x10000
	s_mov_b32 s24, 0x18000
	s_mov_b32 s25, 0x20000
	s_mov_b32 s26, 0xff61b1e6
	v_add_u32_e32 v198, v5, v2
	v_add_u32_e32 v199, v10, v11
	v_add_u32_e32 v201, v12, v13
	v_lshlrev_b32_e32 v188, 1, v4
	v_add_u32_e32 v202, v8, v9
	v_mbcnt_hi_u32_b32 v203, -1, v1
	s_mov_b32 s27, s2
	v_lshrrev_b32_e32 v237, 3, v200
	v_and_b32_e32 v238, 7, v200
	v_bfe_u32 v239, v200, 4, 3
	v_xor_b32_e32 v238, v238, v239
	v_lshlrev_b32_e32 v238, 4, v238
	v_lshl_add_u32 v199, v237, 7, v238
	v_and_b32_e32 v237, 15, v200
	v_bfe_u32 v238, v200, 4, 2
	v_bfe_u32 v239, v200, 1, 3
	v_xor_b32_e32 v238, v238, v239
	v_lshlrev_b32_e32 v238, 4, v238
	v_lshl_add_u32 v201, v237, 7, v238
	v_xor_b32_e32 v239, 64, v201
	s_branch .LBB0_1084

; #define LAS __attribute__((address_space(3)))
; #define LOADV(i) do { _Pragma("unroll") for (int j = 0; j < 4; ++j) st[j] = *(const u32x4*)(vbase + (j * 64 * 256 + (i) * 64) + voff); } while (0)
; #define STOREV() do { _Pragma("unroll") for (int j = 0; j < 4; ++j) *(LAS u32x4*)(vst + j * 64 * 144) = st[j]; } while (0)
; __device__ __forceinline__ void ph_attn(const Params& p, LAS unsigned char* lds) {
;     ...
; #pragma unroll 1
;         for (int i = 0; i < 4; ++i) {
;             __syncthreads(); STOREV(); __syncthreads();
;             if (i < 3) LOADV(i + 1);
;             if (active) {
; #pragma unroll
;                 for (int ks = 0; ks < 2; ++ks) {
;                     const bf16x8 pf = *(const LAS bf16x8*)(pw + fq * 8 + i * 128 + ks * 64);
; #pragma unroll
;                     for (int dt = 0; dt < 16; ++dt) {
;                         const bf16x8 vf = *(const LAS bf16x8*)(vrd + dt * 16 * 144 + ks * 64);
;                         oa[dt] = __builtin_amdgcn_mfma_f32_16x16x32_bf16(vf, pf, oa[dt], 0, 0, 0);
;                     }
;                 }
;             }
;         }
.LBB0_1104:
	s_waitcnt lgkmcnt(0)
	s_barrier
	s_waitcnt vmcnt(7)
	ds_write_b128 v199, v[100:103]
	s_waitcnt vmcnt(6)
	ds_write_b128 v199, v[104:107] offset:8192
	s_waitcnt vmcnt(5)
	ds_write_b128 v199, v[108:111] offset:16384
	s_waitcnt vmcnt(4)
	ds_write_b128 v199, v[112:115] offset:24576
	v_mov_b32_e32 v100, v238
	v_add_u32_e32 v104, 0x8000, v238
	v_add_u32_e32 v108, 0x10000, v238
	v_add_u32_e32 v112, 0x18000, v238
	s_waitcnt lgkmcnt(0)
	s_barrier
	global_load_dwordx4 v[100:103], v100, s[100:101] offset:256
	global_load_dwordx4 v[104:107], v104, s[100:101] offset:256
	global_load_dwordx4 v[108:111], v108, s[100:101] offset:256
	global_load_dwordx4 v[112:115], v112, s[100:101] offset:256
	s_and_b64 vcc, exec, s[4:5]
	s_cbranch_vccnz .Lat_pv1
	ds_read_b128 v[208:211], v187
	ds_read_b128 v[212:215], v187 offset:64
	ds_read_b128 v[36:39], v201
	ds_read_b128 v[40:43], v201 offset:2048
	ds_read_b128 v[44:47], v201 offset:4096
	ds_read_b128 v[48:51], v201 offset:6144
	ds_read_b128 v[52:55], v201 offset:8192
	ds_read_b128 v[56:59], v201 offset:10240
	ds_read_b128 v[60:63], v201 offset:12288
	ds_read_b128 v[64:67], v201 offset:14336
	s_waitcnt lgkmcnt(7)
	v_mfma_f32_16x16x32_bf16 v[176:179], v[36:39], v[208:211], v[176:179]
	ds_read_b128 v[68:71], v201 offset:16384
	s_waitcnt lgkmcnt(7)
	v_mfma_f32_16x16x32_bf16 v[172:175], v[40:43], v[208:211], v[172:175]
	ds_read_b128 v[72:75], v201 offset:18432
	s_waitcnt lgkmcnt(7)
	v_mfma_f32_16x16x32_bf16 v[168:171], v[44:47], v[208:211], v[168:171]
	ds_read_b128 v[76:79], v201 offset:20480
	s_waitcnt lgkmcnt(7)
	v_mfma_f32_16x16x32_bf16 v[164:167], v[48:51], v[208:211], v[164:167]
	ds_read_b128 v[80:83], v201 offset:22528
	s_waitcnt lgkmcnt(7)
	v_mfma_f32_16x16x32_bf16 v[160:163], v[52:55], v[208:211], v[160:163]
	ds_read_b128 v[84:87], v201 offset:24576
	s_waitcnt lgkmcnt(7)
	v_mfma_f32_16x16x32_bf16 v[156:159], v[56:59], v[208:211], v[156:159]
	ds_read_b128 v[88:91], v201 offset:26624
	s_waitcnt lgkmcnt(7)
	v_mfma_f32_16x16x32_bf16 v[152:155], v[60:63], v[208:211], v[152:155]
	ds_read_b128 v[92:95], v201 offset:28672
	s_waitcnt lgkmcnt(7)
	v_mfma_f32_16x16x32_bf16 v[148:151], v[64:67], v[208:211], v[148:151]
	ds_read_b128 v[96:99], v201 offset:30720
	s_waitcnt lgkmcnt(7)
	v_mfma_f32_16x16x32_bf16 v[144:147], v[68:71], v[208:211], v[144:147]
	ds_read_b128 v[36:39], v239
	s_waitcnt lgkmcnt(7)
	v_mfma_f32_16x16x32_bf16 v[140:143], v[72:75], v[208:211], v[140:143]
	ds_read_b128 v[40:43], v239 offset:2048
	s_waitcnt lgkmcnt(7)
	v_mfma_f32_16x16x32_bf16 v[136:139], v[76:79], v[208:211], v[136:139]
	ds_read_b128 v[44:47], v239 offset:4096
	s_waitcnt lgkmcnt(7)
	v_mfma_f32_16x16x32_bf16 v[132:135], v[80:83], v[208:211], v[132:135]
	ds_read_b128 v[48:51], v239 offset:6144
	s_waitcnt lgkmcnt(7)
	v_mfma_f32_16x16x32_bf16 v[128:131], v[84:87], v[208:211], v[128:131]
	ds_read_b128 v[52:55], v239 offset:8192
	s_waitcnt lgkmcnt(7)
	v_mfma_f32_16x16x32_bf16 v[124:127], v[88:91], v[208:211], v[124:127]
	ds_read_b128 v[56:59], v239 offset:10240
	s_waitcnt lgkmcnt(7)
	v_mfma_f32_16x16x32_bf16 v[120:123], v[92:95], v[208:211], v[120:123]
	ds_read_b128 v[60:63], v239 offset:12288
	s_waitcnt lgkmcnt(7)
	v_mfma_f32_16x16x32_bf16 v[116:119], v[96:99], v[208:211], v[116:119]
	ds_read_b128 v[64:67], v239 offset:14336
	s_waitcnt lgkmcnt(7)
	v_mfma_f32_16x16x32_bf16 v[176:179], v[36:39], v[212:215], v[176:179]
	ds_read_b128 v[68:71], v239 offset:16384
	s_waitcnt lgkmcnt(7)
	v_mfma_f32_16x16x32_bf16 v[172:175], v[40:43], v[212:215], v[172:175]
	ds_read_b128 v[72:75], v239 offset:18432
	s_waitcnt lgkmcnt(7)
	v_mfma_f32_16x16x32_bf16 v[168:171], v[44:47], v[212:215], v[168:171]
	ds_read_b128 v[76:79], v239 offset:20480
	s_waitcnt lgkmcnt(7)
	v_mfma_f32_16x16x32_bf16 v[164:167], v[48:51], v[212:215], v[164:167]
	ds_read_b128 v[80:83], v239 offset:22528
	s_waitcnt lgkmcnt(7)
	v_mfma_f32_16x16x32_bf16 v[160:163], v[52:55], v[212:215], v[160:163]
	ds_read_b128 v[84:87], v239 offset:24576
	s_waitcnt lgkmcnt(7)
	v_mfma_f32_16x16x32_bf16 v[156:159], v[56:59], v[212:215], v[156:159]
	ds_read_b128 v[88:91], v239 offset:26624
	s_waitcnt lgkmcnt(7)
	v_mfma_f32_16x16x32_bf16 v[152:155], v[60:63], v[212:215], v[152:155]
	ds_read_b128 v[92:95], v239 offset:28672
	s_waitcnt lgkmcnt(7)
	v_mfma_f32_16x16x32_bf16 v[148:151], v[64:67], v[212:215], v[148:151]
	ds_read_b128 v[96:99], v239 offset:30720
	s_waitcnt lgkmcnt(7)
	v_mfma_f32_16x16x32_bf16 v[144:147], v[68:71], v[212:215], v[144:147]
	s_waitcnt lgkmcnt(6)
	v_mfma_f32_16x16x32_bf16 v[140:143], v[72:75], v[212:215], v[140:143]
	s_waitcnt lgkmcnt(5)
	v_mfma_f32_16x16x32_bf16 v[136:139], v[76:79], v[212:215], v[136:139]
	s_waitcnt lgkmcnt(4)
	v_mfma_f32_16x16x32_bf16 v[132:135], v[80:83], v[212:215], v[132:135]
	s_waitcnt lgkmcnt(3)
	v_mfma_f32_16x16x32_bf16 v[128:131], v[84:87], v[212:215], v[128:131]
	s_waitcnt lgkmcnt(2)
	v_mfma_f32_16x16x32_bf16 v[124:127], v[88:91], v[212:215], v[124:127]
	s_waitcnt lgkmcnt(1)
	v_mfma_f32_16x16x32_bf16 v[120:123], v[92:95], v[212:215], v[120:123]
	s_waitcnt lgkmcnt(0)
	v_mfma_f32_16x16x32_bf16 v[116:119], v[96:99], v[212:215], v[116:119]
; #define LAS __attribute__((address_space(3)))
; #define LOADV(i) do { _Pragma("unroll") for (int j = 0; j < 4; ++j) st[j] = *(const u32x4*)(vbase + (j * 64 * 256 + (i) * 64) + voff); } while (0)
; #define STOREV() do { _Pragma("unroll") for (int j = 0; j < 4; ++j) *(LAS u32x4*)(vst + j * 64 * 144) = st[j]; } while (0)
; __device__ __forceinline__ void ph_attn(const Params& p, LAS unsigned char* lds) {
;     ...
; #pragma unroll 1
;         for (int i = 0; i < 4; ++i) {
;             __syncthreads(); STOREV(); __syncthreads();
;             if (i < 3) LOADV(i + 1);
;             if (active) {
; #pragma unroll
;                 for (int ks = 0; ks < 2; ++ks) {
;                     const bf16x8 pf = *(const LAS bf16x8*)(pw + fq * 8 + i * 128 + ks * 64);
; #pragma unroll
;                     for (int dt = 0; dt < 16; ++dt) {
;                         const bf16x8 vf = *(const LAS bf16x8*)(vrd + dt * 16 * 144 + ks * 64);
;                         oa[dt] = __builtin_amdgcn_mfma_f32_16x16x32_bf16(vf, pf, oa[dt], 0, 0, 0);
;                     }
;                 }
;             }
;         }
.Lat_pv1:
	s_waitcnt lgkmcnt(0)
	s_barrier
	s_waitcnt vmcnt(7)
	ds_write_b128 v199, v[240:243]
	s_waitcnt vmcnt(6)
	ds_write_b128 v199, v[244:247] offset:8192
	s_waitcnt vmcnt(5)
	ds_write_b128 v199, v[248:251] offset:16384
	s_waitcnt vmcnt(4)
	ds_write_b128 v199, v[252:255] offset:24576
	v_mov_b32_e32 v240, v238
	v_add_u32_e32 v244, 0x8000, v238
	v_add_u32_e32 v248, 0x10000, v238
	v_add_u32_e32 v252, 0x18000, v238
	s_waitcnt lgkmcnt(0)
	s_barrier
	global_load_dwordx4 v[240:243], v240, s[100:101] offset:384
	global_load_dwordx4 v[244:247], v244, s[100:101] offset:384
	global_load_dwordx4 v[248:251], v248, s[100:101] offset:384
	global_load_dwordx4 v[252:255], v252, s[100:101] offset:384
	s_and_b64 vcc, exec, s[4:5]
	s_cbranch_vccnz .Lat_pv2
	ds_read_b128 v[208:211], v187 offset:128
	ds_read_b128 v[212:215], v187 offset:192
	ds_read_b128 v[36:39], v201
	ds_read_b128 v[40:43], v201 offset:2048
	ds_read_b128 v[44:47], v201 offset:4096
	ds_read_b128 v[48:51], v201 offset:6144
	ds_read_b128 v[52:55], v201 offset:8192
	ds_read_b128 v[56:59], v201 offset:10240
	ds_read_b128 v[60:63], v201 offset:12288
	ds_read_b128 v[64:67], v201 offset:14336
	s_waitcnt lgkmcnt(7)
	v_mfma_f32_16x16x32_bf16 v[176:179], v[36:39], v[208:211], v[176:179]
	ds_read_b128 v[68:71], v201 offset:16384
	s_waitcnt lgkmcnt(7)
	v_mfma_f32_16x16x32_bf16 v[172:175], v[40:43], v[208:211], v[172:175]
	ds_read_b128 v[72:75], v201 offset:18432
	s_waitcnt lgkmcnt(7)
	v_mfma_f32_16x16x32_bf16 v[168:171], v[44:47], v[208:211], v[168:171]
	ds_read_b128 v[76:79], v201 offset:20480
	s_waitcnt lgkmcnt(7)
	v_mfma_f32_16x16x32_bf16 v[164:167], v[48:51], v[208:211], v[164:167]
	ds_read_b128 v[80:83], v201 offset:22528
	s_waitcnt lgkmcnt(7)
	v_mfma_f32_16x16x32_bf16 v[160:163], v[52:55], v[208:211], v[160:163]
	ds_read_b128 v[84:87], v201 offset:24576
	s_waitcnt lgkmcnt(7)
	v_mfma_f32_16x16x32_bf16 v[156:159], v[56:59], v[208:211], v[156:159]
	ds_read_b128 v[88:91], v201 offset:26624
	s_waitcnt lgkmcnt(7)
	v_mfma_f32_16x16x32_bf16 v[152:155], v[60:63], v[208:211], v[152:155]
	ds_read_b128 v[92:95], v201 offset:28672
	s_waitcnt lgkmcnt(7)
	v_mfma_f32_16x16x32_bf16 v[148:151], v[64:67], v[208:211], v[148:151]
	ds_read_b128 v[96:99], v201 offset:30720
	s_waitcnt lgkmcnt(7)
	v_mfma_f32_16x16x32_bf16 v[144:147], v[68:71], v[208:211], v[144:147]
	ds_read_b128 v[36:39], v239
	s_waitcnt lgkmcnt(7)
	v_mfma_f32_16x16x32_bf16 v[140:143], v[72:75], v[208:211], v[140:143]
	ds_read_b128 v[40:43], v239 offset:2048
	s_waitcnt lgkmcnt(7)
	v_mfma_f32_16x16x32_bf16 v[136:139], v[76:79], v[208:211], v[136:139]
	ds_read_b128 v[44:47], v239 offset:4096
	s_waitcnt lgkmcnt(7)
	v_mfma_f32_16x16x32_bf16 v[132:135], v[80:83], v[208:211], v[132:135]
	ds_read_b128 v[48:51], v239 offset:6144
	s_waitcnt lgkmcnt(7)
	v_mfma_f32_16x16x32_bf16 v[128:131], v[84:87], v[208:211], v[128:131]
	ds_read_b128 v[52:55], v239 offset:8192
	s_waitcnt lgkmcnt(7)
	v_mfma_f32_16x16x32_bf16 v[124:127], v[88:91], v[208:211], v[124:127]
	ds_read_b128 v[56:59], v239 offset:10240
	s_waitcnt lgkmcnt(7)
	v_mfma_f32_16x16x32_bf16 v[120:123], v[92:95], v[208:211], v[120:123]
	ds_read_b128 v[60:63], v239 offset:12288
	s_waitcnt lgkmcnt(7)
	v_mfma_f32_16x16x32_bf16 v[116:119], v[96:99], v[208:211], v[116:119]
	ds_read_b128 v[64:67], v239 offset:14336
	s_waitcnt lgkmcnt(7)
	v_mfma_f32_16x16x32_bf16 v[176:179], v[36:39], v[212:215], v[176:179]
	ds_read_b128 v[68:71], v239 offset:16384
	s_waitcnt lgkmcnt(7)
	v_mfma_f32_16x16x32_bf16 v[172:175], v[40:43], v[212:215], v[172:175]
	ds_read_b128 v[72:75], v239 offset:18432
	s_waitcnt lgkmcnt(7)
	v_mfma_f32_16x16x32_bf16 v[168:171], v[44:47], v[212:215], v[168:171]
	ds_read_b128 v[76:79], v239 offset:20480
	s_waitcnt lgkmcnt(7)
	v_mfma_f32_16x16x32_bf16 v[164:167], v[48:51], v[212:215], v[164:167]
	ds_read_b128 v[80:83], v239 offset:22528
	s_waitcnt lgkmcnt(7)
	v_mfma_f32_16x16x32_bf16 v[160:163], v[52:55], v[212:215], v[160:163]
	ds_read_b128 v[84:87], v239 offset:24576
	s_waitcnt lgkmcnt(7)
	v_mfma_f32_16x16x32_bf16 v[156:159], v[56:59], v[212:215], v[156:159]
	ds_read_b128 v[88:91], v239 offset:26624
	s_waitcnt lgkmcnt(7)
	v_mfma_f32_16x16x32_bf16 v[152:155], v[60:63], v[212:215], v[152:155]
	ds_read_b128 v[92:95], v239 offset:28672
	s_waitcnt lgkmcnt(7)
	v_mfma_f32_16x16x32_bf16 v[148:151], v[64:67], v[212:215], v[148:151]
	ds_read_b128 v[96:99], v239 offset:30720
	s_waitcnt lgkmcnt(7)
	v_mfma_f32_16x16x32_bf16 v[144:147], v[68:71], v[212:215], v[144:147]
	s_waitcnt lgkmcnt(6)
	v_mfma_f32_16x16x32_bf16 v[140:143], v[72:75], v[212:215], v[140:143]
	s_waitcnt lgkmcnt(5)
	v_mfma_f32_16x16x32_bf16 v[136:139], v[76:79], v[212:215], v[136:139]
	s_waitcnt lgkmcnt(4)
	v_mfma_f32_16x16x32_bf16 v[132:135], v[80:83], v[212:215], v[132:135]
	s_waitcnt lgkmcnt(3)
	v_mfma_f32_16x16x32_bf16 v[128:131], v[84:87], v[212:215], v[128:131]
	s_waitcnt lgkmcnt(2)
	v_mfma_f32_16x16x32_bf16 v[124:127], v[88:91], v[212:215], v[124:127]
	s_waitcnt lgkmcnt(1)
	v_mfma_f32_16x16x32_bf16 v[120:123], v[92:95], v[212:215], v[120:123]
	s_waitcnt lgkmcnt(0)
	v_mfma_f32_16x16x32_bf16 v[116:119], v[96:99], v[212:215], v[116:119]
; #define LAS __attribute__((address_space(3)))
; #define LOADV(i) do { _Pragma("unroll") for (int j = 0; j < 4; ++j) st[j] = *(const u32x4*)(vbase + (j * 64 * 256 + (i) * 64) + voff); } while (0)
; #define STOREV() do { _Pragma("unroll") for (int j = 0; j < 4; ++j) *(LAS u32x4*)(vst + j * 64 * 144) = st[j]; } while (0)
; __device__ __forceinline__ void ph_attn(const Params& p, LAS unsigned char* lds) {
;     ...
; #pragma unroll 1
;         for (int i = 0; i < 4; ++i) {
;             __syncthreads(); STOREV(); __syncthreads();
;             if (i < 3) LOADV(i + 1);
;             if (active) {
; #pragma unroll
;                 for (int ks = 0; ks < 2; ++ks) {
;                     const bf16x8 pf = *(const LAS bf16x8*)(pw + fq * 8 + i * 128 + ks * 64);
; #pragma unroll
;                     for (int dt = 0; dt < 16; ++dt) {
;                         const bf16x8 vf = *(const LAS bf16x8*)(vrd + dt * 16 * 144 + ks * 64);
;                         oa[dt] = __builtin_amdgcn_mfma_f32_16x16x32_bf16(vf, pf, oa[dt], 0, 0, 0);
;                     }
;                 }
;             }
;         }
.Lat_pv2:
	s_waitcnt lgkmcnt(0)
	s_barrier
	s_waitcnt vmcnt(7)
	ds_write_b128 v199, v[100:103]
	s_waitcnt vmcnt(6)
	ds_write_b128 v199, v[104:107] offset:8192
	s_waitcnt vmcnt(5)
	ds_write_b128 v199, v[108:111] offset:16384
	s_waitcnt vmcnt(4)
	ds_write_b128 v199, v[112:115] offset:24576
	s_waitcnt lgkmcnt(0)
	s_barrier
	s_and_b64 vcc, exec, s[4:5]
	s_cbranch_vccnz .Lat_pv3
	ds_read_b128 v[208:211], v187 offset:256
	ds_read_b128 v[212:215], v187 offset:320
	ds_read_b128 v[36:39], v201
	ds_read_b128 v[40:43], v201 offset:2048
	ds_read_b128 v[44:47], v201 offset:4096
	ds_read_b128 v[48:51], v201 offset:6144
	ds_read_b128 v[52:55], v201 offset:8192
	ds_read_b128 v[56:59], v201 offset:10240
	ds_read_b128 v[60:63], v201 offset:12288
	ds_read_b128 v[64:67], v201 offset:14336
	s_waitcnt lgkmcnt(7)
	v_mfma_f32_16x16x32_bf16 v[176:179], v[36:39], v[208:211], v[176:179]
	ds_read_b128 v[68:71], v201 offset:16384
	s_waitcnt lgkmcnt(7)
	v_mfma_f32_16x16x32_bf16 v[172:175], v[40:43], v[208:211], v[172:175]
	ds_read_b128 v[72:75], v201 offset:18432
	s_waitcnt lgkmcnt(7)
	v_mfma_f32_16x16x32_bf16 v[168:171], v[44:47], v[208:211], v[168:171]
	ds_read_b128 v[76:79], v201 offset:20480
	s_waitcnt lgkmcnt(7)
	v_mfma_f32_16x16x32_bf16 v[164:167], v[48:51], v[208:211], v[164:167]
	ds_read_b128 v[80:83], v201 offset:22528
	s_waitcnt lgkmcnt(7)
	v_mfma_f32_16x16x32_bf16 v[160:163], v[52:55], v[208:211], v[160:163]
	ds_read_b128 v[84:87], v201 offset:24576
	s_waitcnt lgkmcnt(7)
	v_mfma_f32_16x16x32_bf16 v[156:159], v[56:59], v[208:211], v[156:159]
	ds_read_b128 v[88:91], v201 offset:26624
	s_waitcnt lgkmcnt(7)
	v_mfma_f32_16x16x32_bf16 v[152:155], v[60:63], v[208:211], v[152:155]
	ds_read_b128 v[92:95], v201 offset:28672
	s_waitcnt lgkmcnt(7)
	v_mfma_f32_16x16x32_bf16 v[148:151], v[64:67], v[208:211], v[148:151]
	ds_read_b128 v[96:99], v201 offset:30720
	s_waitcnt lgkmcnt(7)
	v_mfma_f32_16x16x32_bf16 v[144:147], v[68:71], v[208:211], v[144:147]
	ds_read_b128 v[36:39], v239
	s_waitcnt lgkmcnt(7)
	v_mfma_f32_16x16x32_bf16 v[140:143], v[72:75], v[208:211], v[140:143]
	ds_read_b128 v[40:43], v239 offset:2048
	s_waitcnt lgkmcnt(7)
	v_mfma_f32_16x16x32_bf16 v[136:139], v[76:79], v[208:211], v[136:139]
	ds_read_b128 v[44:47], v239 offset:4096
	s_waitcnt lgkmcnt(7)
	v_mfma_f32_16x16x32_bf16 v[132:135], v[80:83], v[208:211], v[132:135]
	ds_read_b128 v[48:51], v239 offset:6144
	s_waitcnt lgkmcnt(7)
	v_mfma_f32_16x16x32_bf16 v[128:131], v[84:87], v[208:211], v[128:131]
	ds_read_b128 v[52:55], v239 offset:8192
	s_waitcnt lgkmcnt(7)
	v_mfma_f32_16x16x32_bf16 v[124:127], v[88:91], v[208:211], v[124:127]
	ds_read_b128 v[56:59], v239 offset:10240
	s_waitcnt lgkmcnt(7)
	v_mfma_f32_16x16x32_bf16 v[120:123], v[92:95], v[208:211], v[120:123]
	ds_read_b128 v[60:63], v239 offset:12288
	s_waitcnt lgkmcnt(7)
	v_mfma_f32_16x16x32_bf16 v[116:119], v[96:99], v[208:211], v[116:119]
	ds_read_b128 v[64:67], v239 offset:14336
	s_waitcnt lgkmcnt(7)
	v_mfma_f32_16x16x32_bf16 v[176:179], v[36:39], v[212:215], v[176:179]
	ds_read_b128 v[68:71], v239 offset:16384
	s_waitcnt lgkmcnt(7)
	v_mfma_f32_16x16x32_bf16 v[172:175], v[40:43], v[212:215], v[172:175]
	ds_read_b128 v[72:75], v239 offset:18432
	s_waitcnt lgkmcnt(7)
	v_mfma_f32_16x16x32_bf16 v[168:171], v[44:47], v[212:215], v[168:171]
	ds_read_b128 v[76:79], v239 offset:20480
	s_waitcnt lgkmcnt(7)
	v_mfma_f32_16x16x32_bf16 v[164:167], v[48:51], v[212:215], v[164:167]
	ds_read_b128 v[80:83], v239 offset:22528
	s_waitcnt lgkmcnt(7)
	v_mfma_f32_16x16x32_bf16 v[160:163], v[52:55], v[212:215], v[160:163]
	ds_read_b128 v[84:87], v239 offset:24576
	s_waitcnt lgkmcnt(7)
	v_mfma_f32_16x16x32_bf16 v[156:159], v[56:59], v[212:215], v[156:159]
	ds_read_b128 v[88:91], v239 offset:26624
	s_waitcnt lgkmcnt(7)
	v_mfma_f32_16x16x32_bf16 v[152:155], v[60:63], v[212:215], v[152:155]
	ds_read_b128 v[92:95], v239 offset:28672
	s_waitcnt lgkmcnt(7)
	v_mfma_f32_16x16x32_bf16 v[148:151], v[64:67], v[212:215], v[148:151]
	ds_read_b128 v[96:99], v239 offset:30720
	s_waitcnt lgkmcnt(7)
	v_mfma_f32_16x16x32_bf16 v[144:147], v[68:71], v[212:215], v[144:147]
	s_waitcnt lgkmcnt(6)
	v_mfma_f32_16x16x32_bf16 v[140:143], v[72:75], v[212:215], v[140:143]
	s_waitcnt lgkmcnt(5)
	v_mfma_f32_16x16x32_bf16 v[136:139], v[76:79], v[212:215], v[136:139]
	s_waitcnt lgkmcnt(4)
	v_mfma_f32_16x16x32_bf16 v[132:135], v[80:83], v[212:215], v[132:135]
	s_waitcnt lgkmcnt(3)
	v_mfma_f32_16x16x32_bf16 v[128:131], v[84:87], v[212:215], v[128:131]
	s_waitcnt lgkmcnt(2)
	v_mfma_f32_16x16x32_bf16 v[124:127], v[88:91], v[212:215], v[124:127]
	s_waitcnt lgkmcnt(1)
	v_mfma_f32_16x16x32_bf16 v[120:123], v[92:95], v[212:215], v[120:123]
	s_waitcnt lgkmcnt(0)
	v_mfma_f32_16x16x32_bf16 v[116:119], v[96:99], v[212:215], v[116:119]
; #define LAS __attribute__((address_space(3)))
; #define LOADV(i) do { _Pragma("unroll") for (int j = 0; j < 4; ++j) st[j] = *(const u32x4*)(vbase + (j * 64 * 256 + (i) * 64) + voff); } while (0)
; #define STOREV() do { _Pragma("unroll") for (int j = 0; j < 4; ++j) *(LAS u32x4*)(vst + j * 64 * 144) = st[j]; } while (0)
; __device__ __forceinline__ void ph_attn(const Params& p, LAS unsigned char* lds) {
;     ...
; #pragma unroll 1
;         for (int i = 0; i < 4; ++i) {
;             __syncthreads(); STOREV(); __syncthreads();
;             if (i < 3) LOADV(i + 1);
;             if (active) {
; #pragma unroll
;                 for (int ks = 0; ks < 2; ++ks) {
;                     const bf16x8 pf = *(const LAS bf16x8*)(pw + fq * 8 + i * 128 + ks * 64);
; #pragma unroll
;                     for (int dt = 0; dt < 16; ++dt) {
;                         const bf16x8 vf = *(const LAS bf16x8*)(vrd + dt * 16 * 144 + ks * 64);
;                         oa[dt] = __builtin_amdgcn_mfma_f32_16x16x32_bf16(vf, pf, oa[dt], 0, 0, 0);
;                     }
;                 }
;             }
;         }
.Lat_pv3:
	s_waitcnt lgkmcnt(0)
	s_barrier
	s_waitcnt vmcnt(3)
	ds_write_b128 v199, v[240:243]
	s_waitcnt vmcnt(2)
	ds_write_b128 v199, v[244:247] offset:8192
	s_waitcnt vmcnt(1)
	ds_write_b128 v199, v[248:251] offset:16384
	s_waitcnt vmcnt(0)
	ds_write_b128 v199, v[252:255] offset:24576
	s_waitcnt lgkmcnt(0)
	s_barrier
	s_and_b64 vcc, exec, s[4:5]
	s_cbranch_vccnz .LBB0_1108
	ds_read_b128 v[208:211], v187 offset:384
	ds_read_b128 v[212:215], v187 offset:448
	ds_read_b128 v[36:39], v201
	ds_read_b128 v[40:43], v201 offset:2048
	ds_read_b128 v[44:47], v201 offset:4096
	ds_read_b128 v[48:51], v201 offset:6144
	ds_read_b128 v[52:55], v201 offset:8192
	ds_read_b128 v[56:59], v201 offset:10240
	ds_read_b128 v[60:63], v201 offset:12288
	ds_read_b128 v[64:67], v201 offset:14336
	s_waitcnt lgkmcnt(7)
	v_mfma_f32_16x16x32_bf16 v[176:179], v[36:39], v[208:211], v[176:179]
	ds_read_b128 v[68:71], v201 offset:16384
	s_waitcnt lgkmcnt(7)
	v_mfma_f32_16x16x32_bf16 v[172:175], v[40:43], v[208:211], v[172:175]
	ds_read_b128 v[72:75], v201 offset:18432
	s_waitcnt lgkmcnt(7)
	v_mfma_f32_16x16x32_bf16 v[168:171], v[44:47], v[208:211], v[168:171]
	ds_read_b128 v[76:79], v201 offset:20480
	s_waitcnt lgkmcnt(7)
	v_mfma_f32_16x16x32_bf16 v[164:167], v[48:51], v[208:211], v[164:167]
	ds_read_b128 v[80:83], v201 offset:22528
	s_waitcnt lgkmcnt(7)
	v_mfma_f32_16x16x32_bf16 v[160:163], v[52:55], v[208:211], v[160:163]
	ds_read_b128 v[84:87], v201 offset:24576
	s_waitcnt lgkmcnt(7)
	v_mfma_f32_16x16x32_bf16 v[156:159], v[56:59], v[208:211], v[156:159]
	ds_read_b128 v[88:91], v201 offset:26624
	s_waitcnt lgkmcnt(7)
	v_mfma_f32_16x16x32_bf16 v[152:155], v[60:63], v[208:211], v[152:155]
	ds_read_b128 v[92:95], v201 offset:28672
	s_waitcnt lgkmcnt(7)
	v_mfma_f32_16x16x32_bf16 v[148:151], v[64:67], v[208:211], v[148:151]
	ds_read_b128 v[96:99], v201 offset:30720
	s_waitcnt lgkmcnt(7)
	v_mfma_f32_16x16x32_bf16 v[144:147], v[68:71], v[208:211], v[144:147]
	ds_read_b128 v[36:39], v239
	s_waitcnt lgkmcnt(7)
	v_mfma_f32_16x16x32_bf16 v[140:143], v[72:75], v[208:211], v[140:143]
	ds_read_b128 v[40:43], v239 offset:2048
	s_waitcnt lgkmcnt(7)
	v_mfma_f32_16x16x32_bf16 v[136:139], v[76:79], v[208:211], v[136:139]
	ds_read_b128 v[44:47], v239 offset:4096
	s_waitcnt lgkmcnt(7)
	v_mfma_f32_16x16x32_bf16 v[132:135], v[80:83], v[208:211], v[132:135]
	ds_read_b128 v[48:51], v239 offset:6144
	s_waitcnt lgkmcnt(7)
	v_mfma_f32_16x16x32_bf16 v[128:131], v[84:87], v[208:211], v[128:131]
	ds_read_b128 v[52:55], v239 offset:8192
	s_waitcnt lgkmcnt(7)
	v_mfma_f32_16x16x32_bf16 v[124:127], v[88:91], v[208:211], v[124:127]
	ds_read_b128 v[56:59], v239 offset:10240
	s_waitcnt lgkmcnt(7)
	v_mfma_f32_16x16x32_bf16 v[120:123], v[92:95], v[208:211], v[120:123]
	ds_read_b128 v[60:63], v239 offset:12288
	s_waitcnt lgkmcnt(7)
	v_mfma_f32_16x16x32_bf16 v[116:119], v[96:99], v[208:211], v[116:119]
	ds_read_b128 v[64:67], v239 offset:14336
	s_waitcnt lgkmcnt(7)
	v_mfma_f32_16x16x32_bf16 v[176:179], v[36:39], v[212:215], v[176:179]
	ds_read_b128 v[68:71], v239 offset:16384
	s_waitcnt lgkmcnt(7)
	v_mfma_f32_16x16x32_bf16 v[172:175], v[40:43], v[212:215], v[172:175]
	ds_read_b128 v[72:75], v239 offset:18432
	s_waitcnt lgkmcnt(7)
	v_mfma_f32_16x16x32_bf16 v[168:171], v[44:47], v[212:215], v[168:171]
	ds_read_b128 v[76:79], v239 offset:20480
	s_waitcnt lgkmcnt(7)
	v_mfma_f32_16x16x32_bf16 v[164:167], v[48:51], v[212:215], v[164:167]
	ds_read_b128 v[80:83], v239 offset:22528
	s_waitcnt lgkmcnt(7)
	v_mfma_f32_16x16x32_bf16 v[160:163], v[52:55], v[212:215], v[160:163]
	ds_read_b128 v[84:87], v239 offset:24576
	s_waitcnt lgkmcnt(7)
	v_mfma_f32_16x16x32_bf16 v[156:159], v[56:59], v[212:215], v[156:159]
	ds_read_b128 v[88:91], v239 offset:26624
	s_waitcnt lgkmcnt(7)
	v_mfma_f32_16x16x32_bf16 v[152:155], v[60:63], v[212:215], v[152:155]
	ds_read_b128 v[92:95], v239 offset:28672
	s_waitcnt lgkmcnt(7)
	v_mfma_f32_16x16x32_bf16 v[148:151], v[64:67], v[212:215], v[148:151]
	ds_read_b128 v[96:99], v239 offset:30720
	s_waitcnt lgkmcnt(7)
	v_mfma_f32_16x16x32_bf16 v[144:147], v[68:71], v[212:215], v[144:147]
	s_waitcnt lgkmcnt(6)
	v_mfma_f32_16x16x32_bf16 v[140:143], v[72:75], v[212:215], v[140:143]
	s_waitcnt lgkmcnt(5)
	v_mfma_f32_16x16x32_bf16 v[136:139], v[76:79], v[212:215], v[136:139]
	s_waitcnt lgkmcnt(4)
	v_mfma_f32_16x16x32_bf16 v[132:135], v[80:83], v[212:215], v[132:135]
	s_waitcnt lgkmcnt(3)
	v_mfma_f32_16x16x32_bf16 v[128:131], v[84:87], v[212:215], v[128:131]
	s_waitcnt lgkmcnt(2)
	v_mfma_f32_16x16x32_bf16 v[124:127], v[88:91], v[212:215], v[124:127]
	s_waitcnt lgkmcnt(1)
	v_mfma_f32_16x16x32_bf16 v[120:123], v[92:95], v[212:215], v[120:123]
	s_waitcnt lgkmcnt(0)
	v_mfma_f32_16x16x32_bf16 v[116:119], v[96:99], v[212:215], v[116:119]
